# MLA: early waves issue their K/V staging DMAs after S MFMAs instead of right after the tile barrier; row max via v_max3 chains
# speedup vs baseline: 1.0201x; 1.0177x over previous
; DI void mla_block(const Params& p, LAS unsigned char* lds, int b, int hd, int qb, int tid) {
;     ...
;     for (int kt = 0; kt < ntiles; ++kt) {
;         asm volatile("s_waitcnt vmcnt(0)" ::: "memory");
;         __builtin_amdgcn_s_barrier();
;         asm volatile("" ::: "memory");
;         const int bprev = bcur == 0 ? 2 : bcur - 1, bnext = bcur == 2 ? 0 : bcur + 1;
;         if (kt + 1 < ntiles) MLA_STAGE(kt + 1, bnext);
.LBB0_622:
	s_add_i32 s76, s73, 1
	s_waitcnt vmcnt(0)
	s_barrier
	s_cmp_lg_u32 s73, 2
	s_cselect_b32 s76, s76, 0
	s_add_i32 s88, s77, 1
	s_cmp_ge_u32 s88, s74
	s_cbranch_scc1 .LBB0_635
	s_andn2_b64 vcc, exec, s[2:3]
	s_cbranch_vccnz .Lmla_stnow_0
	s_cmp_gt_i32 s77, s33
	s_cbranch_scc0 .LBB0_635
.Lmla_stnow_0:
	s_mul_i32 s89, s76, 0xac00
	s_andn2_b64 vcc, exec, s[80:81]
	s_add_i32 s89, s89, 0
	s_cbranch_vccnz .LBB0_629
	v_readlane_b32 s90, v255, 11
	v_lshl_add_u32 v0, s88, v176, v166
	s_add_i32 m0, s89, s90
	s_nop 0
	global_load_lds_dwordx4 v0, s[12:13]
	s_andn2_b64 vcc, exec, s[82:83]
	s_cbranch_vccz .LBB0_630

; DI void mla_block(const Params& p, LAS unsigned char* lds, int b, int hd, int qb, int tid) {
;     ...
;         if (kt + 1 < ntiles) MLA_STAGE(kt + 1, bnext);
.LBB0_641:
	s_andn2_b64 vcc, exec, s[2:3]
	s_cbranch_vccnz .Lmla_no_vpre_0
	s_cmp_ge_u32 s88, s74
	s_cbranch_scc1 .Lmla_dst0_done
	s_mul_i32 s89, s76, 0xac00
	s_andn2_b64 vcc, exec, s[80:81]
	s_add_i32 s89, s89, 0
	s_cbranch_vccnz .Lmla_dst0_629
	v_readlane_b32 s90, v255, 11
	v_lshl_add_u32 v0, s88, v176, v166
	s_add_i32 m0, s89, s90
	s_nop 0
	global_load_lds_dwordx4 v0, s[12:13]
	s_andn2_b64 vcc, exec, s[82:83]
	s_cbranch_vccz .Lmla_dst0_630

; DI float xhalf_max(float x) { float lo, hi; xhalf(x, lo, hi); return fmaxf(lo, hi); }
; DI void mla_s_softmax(const LAS unsigned char* base, int r, int h, bool is_diag, int lim, const bf16x8 (&qf)[12], f32x16 (&o)[4], float& m_run, float& l_run,
;                       bf16x8 (&pf0)[2], bf16x8 (&pf1)[2]) {
;     ...
;     float mx = fmaxf(s0[0], s1[0]);
; #pragma unroll
;     for (int i = 1; i < 16; ++i) mx = fmaxf(mx, fmaxf(s0[i], s1[i]));
;     mx = xhalf_max(mx);
;     const float mnew = fmaxf(m_run, mx);
;     if (__builtin_amdgcn_ballot_w64(mnew > m_run + 8.0f) != 0ull) {
;         const float alpha = __builtin_amdgcn_exp2f(m_run - mnew);
;         l_run *= alpha;
; #pragma unroll
;         for (int dt = 0; dt < 4; ++dt) o[dt] *= alpha;
;         m_run = mnew;
;     }
.Lmla_dst0_done:
	v_add3_u32 v252, s73, v172, v173
	ds_read_b128 v[232:235], v252 offset:25616
	ds_read_b128 v[236:239], v252 offset:30224
	ds_read_b128 v[240:243], v252 offset:34832
	ds_read_b128 v[244:247], v252 offset:39440
	ds_read_b128 v[248:251], v252 offset:25680
	ds_read_b128 v[200:203], v252 offset:25600
	ds_read_b128 v[204:207], v252 offset:25664
	ds_read_b128 v[208:211], v252 offset:30208
	ds_read_b128 v[212:215], v252 offset:30272
	ds_read_b128 v[216:219], v252 offset:34816
	ds_read_b128 v[220:223], v252 offset:34880
	ds_read_b128 v[224:227], v252 offset:39424
	ds_read_b128 v[228:231], v252 offset:39488
.Lmla_no_vpre_0:
	s_nop 10
	v_max3_f32 v0, v80, v81, v82
	v_max3_f32 v2, v96, v97, v98
	v_max3_f32 v0, v0, v83, v84
	v_max3_f32 v2, v2, v99, v100
	v_max3_f32 v0, v0, v85, v86
	v_max3_f32 v2, v2, v101, v102
	v_max3_f32 v0, v0, v87, v88
	v_max3_f32 v2, v2, v103, v104
	v_max3_f32 v0, v0, v89, v90
	v_max3_f32 v2, v2, v105, v106
	v_max3_f32 v0, v0, v91, v92
	v_max3_f32 v2, v2, v107, v108
	v_max3_f32 v0, v0, v93, v94
	v_max3_f32 v2, v2, v109, v110
	v_max3_f32 v0, v0, v95, v111
	v_max_f32_e32 v0, v0, v2
	v_mov_b32_e32 v2, v0
	s_nop 1
	v_permlane32_swap_b32_e32 v0, v2
	v_max3_f32 v0, v183, v0, v2
	v_add_f32_e32 v2, 0x41000000, v183
	v_cmp_gt_f32_e32 vcc, v0, v2
	s_cbranch_vccz .LBB0_643
	v_sub_f32_e32 v2, v183, v0
	v_exp_f32_e32 v2, v2
	v_mov_b32_e32 v183, v0
	v_mul_f32_e32 v175, v175, v2
	v_pk_mul_f32 v[78:79], v[78:79], v[2:3] op_sel_hi:[1,0]
	v_pk_mul_f32 v[76:77], v[76:77], v[2:3] op_sel_hi:[1,0]
	v_pk_mul_f32 v[74:75], v[74:75], v[2:3] op_sel_hi:[1,0]
	v_pk_mul_f32 v[72:73], v[72:73], v[2:3] op_sel_hi:[1,0]
	v_pk_mul_f32 v[70:71], v[70:71], v[2:3] op_sel_hi:[1,0]
	v_pk_mul_f32 v[68:69], v[68:69], v[2:3] op_sel_hi:[1,0]
	v_pk_mul_f32 v[66:67], v[66:67], v[2:3] op_sel_hi:[1,0]
	v_pk_mul_f32 v[64:65], v[64:65], v[2:3] op_sel_hi:[1,0]
	v_pk_mul_f32 v[62:63], v[62:63], v[2:3] op_sel_hi:[1,0]
	v_pk_mul_f32 v[60:61], v[60:61], v[2:3] op_sel_hi:[1,0]
	v_pk_mul_f32 v[58:59], v[58:59], v[2:3] op_sel_hi:[1,0]
	v_pk_mul_f32 v[56:57], v[56:57], v[2:3] op_sel_hi:[1,0]
	v_pk_mul_f32 v[54:55], v[54:55], v[2:3] op_sel_hi:[1,0]
	v_pk_mul_f32 v[52:53], v[52:53], v[2:3] op_sel_hi:[1,0]
	v_pk_mul_f32 v[50:51], v[50:51], v[2:3] op_sel_hi:[1,0]
	v_pk_mul_f32 v[48:49], v[48:49], v[2:3] op_sel_hi:[1,0]
	v_pk_mul_f32 v[46:47], v[46:47], v[2:3] op_sel_hi:[1,0]
	v_pk_mul_f32 v[44:45], v[44:45], v[2:3] op_sel_hi:[1,0]
	v_pk_mul_f32 v[42:43], v[42:43], v[2:3] op_sel_hi:[1,0]
	v_pk_mul_f32 v[40:41], v[40:41], v[2:3] op_sel_hi:[1,0]
	v_pk_mul_f32 v[38:39], v[38:39], v[2:3] op_sel_hi:[1,0]
	v_pk_mul_f32 v[36:37], v[36:37], v[2:3] op_sel_hi:[1,0]
	v_pk_mul_f32 v[34:35], v[34:35], v[2:3] op_sel_hi:[1,0]
	v_pk_mul_f32 v[32:33], v[32:33], v[2:3] op_sel_hi:[1,0]
	v_pk_mul_f32 v[30:31], v[30:31], v[2:3] op_sel_hi:[1,0]
	v_pk_mul_f32 v[28:29], v[28:29], v[2:3] op_sel_hi:[1,0]
	v_pk_mul_f32 v[26:27], v[26:27], v[2:3] op_sel_hi:[1,0]
	v_pk_mul_f32 v[24:25], v[24:25], v[2:3] op_sel_hi:[1,0]
	v_pk_mul_f32 v[22:23], v[22:23], v[2:3] op_sel_hi:[1,0]
	v_pk_mul_f32 v[20:21], v[20:21], v[2:3] op_sel_hi:[1,0]
	v_pk_mul_f32 v[18:19], v[18:19], v[2:3] op_sel_hi:[1,0]
	v_pk_mul_f32 v[16:17], v[16:17], v[2:3] op_sel_hi:[1,0]

; DI void mla_block(const Params& p, LAS unsigned char* lds, int b, int hd, int qb, int tid) {
;     ...
;     for (int kt = 0; kt < ntiles; ++kt) {
;         asm volatile("s_waitcnt vmcnt(0)" ::: "memory");
;         __builtin_amdgcn_s_barrier();
;         asm volatile("" ::: "memory");
;         const int bprev = bcur == 0 ? 2 : bcur - 1, bnext = bcur == 2 ? 0 : bcur + 1;
;         if (kt + 1 < ntiles) MLA_STAGE(kt + 1, bnext);
.LBB0_724:
	s_add_i32 s76, s87, 1
	s_waitcnt vmcnt(0)
	s_barrier
	s_cmp_lg_u32 s87, 2
	s_cselect_b32 s76, s76, 0
	s_add_i32 s77, s88, 1
	s_cmp_ge_u32 s77, s73
	s_cbranch_scc1 .LBB0_737
	s_andn2_b64 vcc, exec, s[2:3]
	s_cbranch_vccnz .Lmla_stnow_1
	s_cmp_gt_i32 s88, s33
	s_cbranch_scc0 .LBB0_737
.Lmla_stnow_1:
	s_mul_i32 s89, s76, 0xac00
	s_andn2_b64 vcc, exec, s[80:81]
	s_add_i32 s89, s89, 0
	s_cbranch_vccnz .LBB0_731
	v_readlane_b32 s90, v255, 9
	v_lshl_add_u32 v0, s77, v176, v166
	s_add_i32 m0, s89, s90
	s_nop 0
	global_load_lds_dwordx4 v0, s[12:13]
	s_andn2_b64 vcc, exec, s[82:83]
	s_cbranch_vccz .LBB0_732

; DI void mla_block(const Params& p, LAS unsigned char* lds, int b, int hd, int qb, int tid) {
;     ...
;         if (kt + 1 < ntiles) MLA_STAGE(kt + 1, bnext);
.LBB0_743:
	s_andn2_b64 vcc, exec, s[2:3]
	s_cbranch_vccnz .Lmla_no_vpre_1
	s_cmp_ge_u32 s77, s73
	s_cbranch_scc1 .Lmla_dst1_done
	s_mul_i32 s89, s76, 0xac00
	s_andn2_b64 vcc, exec, s[80:81]
	s_add_i32 s89, s89, 0
	s_cbranch_vccnz .Lmla_dst1_731
	v_readlane_b32 s90, v255, 9
	v_lshl_add_u32 v0, s77, v176, v166
	s_add_i32 m0, s89, s90
	s_nop 0
	global_load_lds_dwordx4 v0, s[12:13]
	s_andn2_b64 vcc, exec, s[82:83]
	s_cbranch_vccz .Lmla_dst1_732

; DI float xhalf_max(float x) { float lo, hi; xhalf(x, lo, hi); return fmaxf(lo, hi); }
; DI void mla_s_softmax(const LAS unsigned char* base, int r, int h, bool is_diag, int lim, const bf16x8 (&qf)[12], f32x16 (&o)[4], float& m_run, float& l_run,
;                       bf16x8 (&pf0)[2], bf16x8 (&pf1)[2]) {
;     ...
;     float mx = fmaxf(s0[0], s1[0]);
; #pragma unroll
;     for (int i = 1; i < 16; ++i) mx = fmaxf(mx, fmaxf(s0[i], s1[i]));
;     mx = xhalf_max(mx);
;     const float mnew = fmaxf(m_run, mx);
;     if (__builtin_amdgcn_ballot_w64(mnew > m_run + 8.0f) != 0ull) {
;         const float alpha = __builtin_amdgcn_exp2f(m_run - mnew);
;         l_run *= alpha;
; #pragma unroll
;         for (int dt = 0; dt < 4; ++dt) o[dt] *= alpha;
;         m_run = mnew;
;     }
.Lmla_dst1_done:
	v_add3_u32 v252, s87, v173, v174
	ds_read_b128 v[232:235], v252 offset:25616
	ds_read_b128 v[236:239], v252 offset:30224
	ds_read_b128 v[240:243], v252 offset:34832
	ds_read_b128 v[244:247], v252 offset:39440
	ds_read_b128 v[248:251], v252 offset:25680
	ds_read_b128 v[200:203], v252 offset:25600
	ds_read_b128 v[204:207], v252 offset:25664
	ds_read_b128 v[208:211], v252 offset:30208
	ds_read_b128 v[212:215], v252 offset:30272
	ds_read_b128 v[216:219], v252 offset:34816
	ds_read_b128 v[220:223], v252 offset:34880
	ds_read_b128 v[224:227], v252 offset:39424
	ds_read_b128 v[228:231], v252 offset:39488
.Lmla_no_vpre_1:
	s_nop 10
	v_max3_f32 v0, v80, v81, v82
	v_max3_f32 v2, v96, v97, v98
	v_max3_f32 v0, v0, v83, v84
	v_max3_f32 v2, v2, v99, v100
	v_max3_f32 v0, v0, v85, v86
	v_max3_f32 v2, v2, v101, v102
	v_max3_f32 v0, v0, v87, v88
	v_max3_f32 v2, v2, v103, v104
	v_max3_f32 v0, v0, v89, v90
	v_max3_f32 v2, v2, v105, v106
	v_max3_f32 v0, v0, v91, v92
	v_max3_f32 v2, v2, v107, v108
	v_max3_f32 v0, v0, v93, v94
	v_max3_f32 v2, v2, v109, v110
	v_max3_f32 v0, v0, v95, v111
	v_max_f32_e32 v0, v0, v2
	v_mov_b32_e32 v2, v0
	s_nop 1
	v_permlane32_swap_b32_e32 v0, v2
	v_max3_f32 v0, v183, v0, v2
	v_add_f32_e32 v2, 0x41000000, v183
	v_cmp_gt_f32_e32 vcc, v0, v2
	s_cbranch_vccz .LBB0_745
	v_sub_f32_e32 v2, v183, v0
	v_exp_f32_e32 v2, v2
	v_mov_b32_e32 v183, v0
	v_mul_f32_e32 v172, v172, v2
	v_pk_mul_f32 v[78:79], v[78:79], v[2:3] op_sel_hi:[1,0]
	v_pk_mul_f32 v[76:77], v[76:77], v[2:3] op_sel_hi:[1,0]
	v_pk_mul_f32 v[74:75], v[74:75], v[2:3] op_sel_hi:[1,0]
	v_pk_mul_f32 v[72:73], v[72:73], v[2:3] op_sel_hi:[1,0]
	v_pk_mul_f32 v[70:71], v[70:71], v[2:3] op_sel_hi:[1,0]
	v_pk_mul_f32 v[68:69], v[68:69], v[2:3] op_sel_hi:[1,0]
	v_pk_mul_f32 v[66:67], v[66:67], v[2:3] op_sel_hi:[1,0]
	v_pk_mul_f32 v[64:65], v[64:65], v[2:3] op_sel_hi:[1,0]
	v_pk_mul_f32 v[62:63], v[62:63], v[2:3] op_sel_hi:[1,0]
	v_pk_mul_f32 v[60:61], v[60:61], v[2:3] op_sel_hi:[1,0]
	v_pk_mul_f32 v[58:59], v[58:59], v[2:3] op_sel_hi:[1,0]
	v_pk_mul_f32 v[56:57], v[56:57], v[2:3] op_sel_hi:[1,0]
	v_pk_mul_f32 v[54:55], v[54:55], v[2:3] op_sel_hi:[1,0]
	v_pk_mul_f32 v[52:53], v[52:53], v[2:3] op_sel_hi:[1,0]
	v_pk_mul_f32 v[50:51], v[50:51], v[2:3] op_sel_hi:[1,0]
	v_pk_mul_f32 v[48:49], v[48:49], v[2:3] op_sel_hi:[1,0]
	v_pk_mul_f32 v[46:47], v[46:47], v[2:3] op_sel_hi:[1,0]
	v_pk_mul_f32 v[44:45], v[44:45], v[2:3] op_sel_hi:[1,0]
	v_pk_mul_f32 v[42:43], v[42:43], v[2:3] op_sel_hi:[1,0]
	v_pk_mul_f32 v[40:41], v[40:41], v[2:3] op_sel_hi:[1,0]
	v_pk_mul_f32 v[38:39], v[38:39], v[2:3] op_sel_hi:[1,0]
	v_pk_mul_f32 v[36:37], v[36:37], v[2:3] op_sel_hi:[1,0]
	v_pk_mul_f32 v[34:35], v[34:35], v[2:3] op_sel_hi:[1,0]
	v_pk_mul_f32 v[32:33], v[32:33], v[2:3] op_sel_hi:[1,0]
	v_pk_mul_f32 v[30:31], v[30:31], v[2:3] op_sel_hi:[1,0]
	v_pk_mul_f32 v[28:29], v[28:29], v[2:3] op_sel_hi:[1,0]
	v_pk_mul_f32 v[26:27], v[26:27], v[2:3] op_sel_hi:[1,0]
	v_pk_mul_f32 v[24:25], v[24:25], v[2:3] op_sel_hi:[1,0]
	v_pk_mul_f32 v[22:23], v[22:23], v[2:3] op_sel_hi:[1,0]
	v_pk_mul_f32 v[20:21], v[20:21], v[2:3] op_sel_hi:[1,0]
	v_pk_mul_f32 v[18:19], v[18:19], v[2:3] op_sel_hi:[1,0]
	v_pk_mul_f32 v[16:17], v[16:17], v[2:3] op_sel_hi:[1,0]
